# pre-loop full VMEM drains before the in-proj and gate-int8 K-loops relaxed to counted waits (epilogue stores may stay in flight)
# baseline (speedup 1.0000x reference)
.LBB0_292:
	s_add_u32 s19, s40, 0x100
	s_addc_u32 s54, s41, 0
	s_add_u32 s55, s38, 0x100
	v_mov_b32_e32 v2, 0
	s_addc_u32 s56, s39, 0
	s_mov_b32 s57, -2
	v_mov_b32_e32 v3, v2
	v_mov_b32_e32 v4, v2
	v_mov_b32_e32 v5, v2
	v_mov_b32_e32 v6, v2
	v_mov_b32_e32 v7, v2
	v_mov_b32_e32 v8, v2
	v_mov_b32_e32 v9, v2
	s_waitcnt vmcnt(8)
	s_cmp_eq_u32 s57, 28
	s_cselect_b32 s42, s10, s19
	s_cselect_b32 s43, s11, s54
	s_cselect_b32 s40, s26, s55
	s_cselect_b32 s41, s27, s56
	s_add_u32 s38, s42, 0x80
	s_addc_u32 s39, s43, 0
	s_add_i32 s60, 0, 0x10000
	s_add_i32 s61, 0, 0x14000
	v_add_u32_e32 v70, s60, v207
	v_add_u32_e32 v110, s61, v207
	ds_read_b128 v[42:45], v70
	ds_read_b128 v[46:49], v70 offset:1024
	ds_read_b128 v[66:69], v70 offset:2048
	ds_read_b128 v[70:73], v70 offset:3072
	ds_read_b128 v[86:89], v110
	ds_read_b128 v[90:93], v110 offset:1024
	ds_read_b128 v[106:109], v110 offset:2048
	ds_read_b128 v[110:113], v110 offset:3072
	s_add_u32 s58, s19, 0x7ff80
	s_addc_u32 s59, s54, 0
	ds_read_b128 v[130:133], v237
	ds_read_b128 v[134:137], v237 offset:1024
	ds_read_b128 v[154:157], v237 offset:2048
	ds_read_b128 v[158:161], v237 offset:3072
	ds_read_b128 v[178:181], v237 offset:4096
	ds_read_b128 v[182:185], v237 offset:5120
	ds_read_b128 v[186:189], v237 offset:6144
	ds_read_b128 v[190:193], v237 offset:7168
	s_add_i32 m0, s46, 0xc000
	v_lshl_add_u64 v[194:195], s[58:59], 0, v[208:209]
	s_add_u32 s58, s58, 0x40000
	s_addc_u32 s59, s59, 0
	global_load_lds_dwordx4 v[194:195], off
	s_add_i32 m0, s46, 0xe000
	v_lshl_add_u64 v[194:195], s[58:59], 0, v[208:209]
	global_load_lds_dwordx4 v[194:195], off
	s_waitcnt vmcnt(8)
	s_waitcnt lgkmcnt(0)
	s_barrier
	v_mfma_f32_16x16x32_bf16 v[174:177], v[42:45], v[130:133], 0
	v_mfma_f32_16x16x32_bf16 v[170:173], v[66:69], v[130:133], 0
	v_mfma_f32_16x16x32_bf16 v[150:153], v[42:45], v[154:157], 0
	v_mfma_f32_16x16x32_bf16 v[146:149], v[66:69], v[154:157], 0
	v_mfma_f32_16x16x32_bf16 v[126:129], v[42:45], v[178:181], 0
	v_mfma_f32_16x16x32_bf16 v[122:125], v[66:69], v[178:181], 0
	v_mfma_f32_16x16x32_bf16 v[102:105], v[42:45], v[186:189], 0
	v_mfma_f32_16x16x32_bf16 v[98:101], v[66:69], v[186:189], 0
	v_mfma_f32_16x16x32_bf16 v[174:177], v[46:49], v[134:137], v[174:177]
	v_mfma_f32_16x16x32_bf16 v[170:173], v[70:73], v[134:137], v[170:173]
	v_mfma_f32_16x16x32_bf16 v[150:153], v[46:49], v[158:161], v[150:153]
	v_mfma_f32_16x16x32_bf16 v[146:149], v[70:73], v[158:161], v[146:149]
	v_mfma_f32_16x16x32_bf16 v[126:129], v[46:49], v[182:185], v[126:129]
	v_mfma_f32_16x16x32_bf16 v[122:125], v[70:73], v[182:185], v[122:125]
	v_mfma_f32_16x16x32_bf16 v[102:105], v[46:49], v[190:193], v[102:105]
	v_mfma_f32_16x16x32_bf16 v[98:101], v[70:73], v[190:193], v[98:101]
	v_mfma_f32_16x16x32_bf16 v[166:169], v[86:89], v[130:133], 0
	v_mfma_f32_16x16x32_bf16 v[130:133], v[106:109], v[130:133], 0
	v_mfma_f32_16x16x32_bf16 v[138:141], v[106:109], v[154:157], 0
	v_mfma_f32_16x16x32_bf16 v[118:121], v[86:89], v[178:181], 0
	v_mfma_f32_16x16x32_bf16 v[114:117], v[106:109], v[178:181], 0
	v_mfma_f32_16x16x32_bf16 v[94:97], v[86:89], v[186:189], 0
	v_mfma_f32_16x16x32_bf16 v[82:85], v[106:109], v[186:189], 0
	v_mfma_f32_16x16x32_bf16 v[166:169], v[90:93], v[134:137], v[166:169]
	v_mfma_f32_16x16x32_bf16 v[130:133], v[110:113], v[134:137], v[130:133]
	v_mfma_f32_16x16x32_bf16 v[134:137], v[86:89], v[154:157], 0
	v_mfma_f32_16x16x32_bf16 v[138:141], v[110:113], v[158:161], v[138:141]
	v_mfma_f32_16x16x32_bf16 v[118:121], v[90:93], v[182:185], v[118:121]
	v_mfma_f32_16x16x32_bf16 v[114:117], v[110:113], v[182:185], v[114:117]
	v_mfma_f32_16x16x32_bf16 v[94:97], v[90:93], v[190:193], v[94:97]
	v_mfma_f32_16x16x32_bf16 v[82:85], v[110:113], v[190:193], v[82:85]
	v_mfma_f32_16x16x32_bf16 v[134:137], v[90:93], v[158:161], v[134:137]
	s_barrier
	s_mov_b64 s[58:59], s[40:41]
	ds_read_b128 v[142:145], v237 offset:16384
	ds_read_b128 v[154:157], v237 offset:17408
	ds_read_b128 v[158:161], v237 offset:18432
	ds_read_b128 v[162:165], v237 offset:19456
	ds_read_b128 v[178:181], v237 offset:20480
	ds_read_b128 v[182:185], v237 offset:21504
	ds_read_b128 v[186:189], v237 offset:22528
	ds_read_b128 v[190:193], v237 offset:23552
	s_add_i32 s60, s60, s45
	v_lshl_add_u64 v[194:195], s[58:59], 0, v[202:203]
	s_add_u32 s58, s58, 0x40000
	s_mov_b32 m0, s60
	s_addc_u32 s59, s59, 0
	global_load_lds_dwordx4 v[194:195], off
	s_add_i32 m0, s60, 0x2000
	v_lshl_add_u64 v[194:195], s[58:59], 0, v[202:203]
	s_add_u32 s58, s40, 0x80000
	s_addc_u32 s59, s41, 0
	global_load_lds_dwordx4 v[194:195], off
	s_add_i32 s60, s61, s45
	v_lshl_add_u64 v[194:195], s[58:59], 0, v[202:203]
	s_add_u32 s58, s58, 0x40000
	s_mov_b32 m0, s60
	s_addc_u32 s59, s59, 0
	global_load_lds_dwordx4 v[194:195], off
	s_add_i32 m0, s60, 0x2000
	v_lshl_add_u64 v[194:195], s[58:59], 0, v[202:203]
	s_mov_b64 s[58:59], s[42:43]
	global_load_lds_dwordx4 v[194:195], off
	s_mov_b32 m0, s46
	v_lshl_add_u64 v[194:195], s[58:59], 0, v[208:209]
	s_add_u32 s58, s58, 0x40000
	s_addc_u32 s59, s59, 0
	global_load_lds_dwordx4 v[194:195], off
	s_mov_b32 m0, s47
	v_lshl_add_u64 v[194:195], s[58:59], 0, v[208:209]
	global_load_lds_dwordx4 v[194:195], off
	s_waitcnt vmcnt(8)
	s_waitcnt lgkmcnt(0)
	s_barrier
	v_mfma_f32_16x16x32_bf16 v[78:81], v[42:45], v[142:145], 0
	v_mfma_f32_16x16x32_bf16 v[74:77], v[66:69], v[142:145], 0
	v_mfma_f32_16x16x32_bf16 v[54:57], v[42:45], v[158:161], 0
	v_mfma_f32_16x16x32_bf16 v[50:53], v[66:69], v[158:161], 0
	v_mfma_f32_16x16x32_bf16 v[30:33], v[42:45], v[178:181], 0
	v_mfma_f32_16x16x32_bf16 v[26:29], v[66:69], v[178:181], 0
	v_mfma_f32_16x16x32_bf16 v[14:17], v[42:45], v[186:189], 0
	v_mfma_f32_16x16x32_bf16 v[10:13], v[66:69], v[186:189], 0
	v_mfma_f32_16x16x32_bf16 v[78:81], v[46:49], v[154:157], v[78:81]
	v_mfma_f32_16x16x32_bf16 v[74:77], v[70:73], v[154:157], v[74:77]
	v_mfma_f32_16x16x32_bf16 v[54:57], v[46:49], v[162:165], v[54:57]
	v_mfma_f32_16x16x32_bf16 v[50:53], v[70:73], v[162:165], v[50:53]
	v_mfma_f32_16x16x32_bf16 v[30:33], v[46:49], v[182:185], v[30:33]
	v_mfma_f32_16x16x32_bf16 v[26:29], v[70:73], v[182:185], v[26:29]
	v_mfma_f32_16x16x32_bf16 v[14:17], v[46:49], v[190:193], v[14:17]
	v_mfma_f32_16x16x32_bf16 v[10:13], v[70:73], v[190:193], v[10:13]
	v_mfma_f32_16x16x32_bf16 v[38:41], v[86:89], v[158:161], 0
	v_mfma_f32_16x16x32_bf16 v[34:37], v[106:109], v[158:161], 0
	v_mfma_f32_16x16x32_bf16 v[22:25], v[86:89], v[178:181], 0
	v_mfma_f32_16x16x32_bf16 v[18:21], v[106:109], v[178:181], 0
	v_mfma_f32_16x16x32_bf16 v[6:9], v[86:89], v[186:189], v[6:9]
	v_mfma_f32_16x16x32_bf16 v[2:5], v[106:109], v[186:189], v[2:5]
	v_mfma_f32_16x16x32_bf16 v[42:45], v[86:89], v[142:145], 0
	v_mfma_f32_16x16x32_bf16 v[46:49], v[106:109], v[142:145], 0
	v_mfma_f32_16x16x32_bf16 v[38:41], v[90:93], v[162:165], v[38:41]
	v_mfma_f32_16x16x32_bf16 v[34:37], v[110:113], v[162:165], v[34:37]
	v_mfma_f32_16x16x32_bf16 v[22:25], v[90:93], v[182:185], v[22:25]
	v_mfma_f32_16x16x32_bf16 v[18:21], v[110:113], v[182:185], v[18:21]
	v_mfma_f32_16x16x32_bf16 v[6:9], v[90:93], v[190:193], v[6:9]
	v_mfma_f32_16x16x32_bf16 v[2:5], v[110:113], v[190:193], v[2:5]
	v_mfma_f32_16x16x32_bf16 v[42:45], v[90:93], v[154:157], v[42:45]
	v_mfma_f32_16x16x32_bf16 v[46:49], v[110:113], v[154:157], v[46:49]
	s_barrier
	s_add_i32 s58, 0, 0x18000
	s_add_i32 s59, 0, 0x1c000
	v_add_u32_e32 v70, s58, v207
	v_add_u32_e32 v110, s59, v207
	ds_read_b128 v[58:61], v70
	ds_read_b128 v[62:65], v70 offset:1024
	ds_read_b128 v[66:69], v70 offset:2048
	ds_read_b128 v[70:73], v70 offset:3072
	ds_read_b128 v[86:89], v110
	ds_read_b128 v[90:93], v110 offset:1024
	ds_read_b128 v[106:109], v110 offset:2048
	ds_read_b128 v[110:113], v110 offset:3072
	s_add_u32 s42, s42, 0x80000
	s_addc_u32 s43, s43, 0
	ds_read_b128 v[142:145], v237 offset:32768
	ds_read_b128 v[154:157], v237 offset:33792
	ds_read_b128 v[158:161], v237 offset:34816
	ds_read_b128 v[178:181], v237 offset:35840
	ds_read_b128 v[182:185], v237 offset:36864
	ds_read_b128 v[186:189], v237 offset:37888
	ds_read_b128 v[190:193], v237 offset:38912
	ds_read_b128 v[194:197], v237 offset:39936
	s_mov_b32 m0, s48
	v_lshl_add_u64 v[162:163], s[42:43], 0, v[208:209]
	s_add_u32 s42, s42, 0x40000
	s_addc_u32 s43, s43, 0
	global_load_lds_dwordx4 v[162:163], off
	s_mov_b32 m0, s49
	v_lshl_add_u64 v[162:163], s[42:43], 0, v[208:209]
	global_load_lds_dwordx4 v[162:163], off
	s_waitcnt vmcnt(8)
	s_waitcnt lgkmcnt(0)
	s_barrier
	v_mfma_f32_16x16x32_bf16 v[162:165], v[58:61], v[142:145], v[174:177]
	v_mfma_f32_16x16x32_bf16 v[174:177], v[62:65], v[154:157], v[162:165]
	v_mfma_f32_16x16x32_bf16 v[162:165], v[66:69], v[142:145], v[170:173]
	v_mfma_f32_16x16x32_bf16 v[150:153], v[58:61], v[158:161], v[150:153]
	v_mfma_f32_16x16x32_bf16 v[146:149], v[66:69], v[158:161], v[146:149]
	v_mfma_f32_16x16x32_bf16 v[126:129], v[58:61], v[182:185], v[126:129]
	v_mfma_f32_16x16x32_bf16 v[122:125], v[66:69], v[182:185], v[122:125]
	v_mfma_f32_16x16x32_bf16 v[102:105], v[58:61], v[190:193], v[102:105]
	v_mfma_f32_16x16x32_bf16 v[98:101], v[66:69], v[190:193], v[98:101]
	v_mfma_f32_16x16x32_bf16 v[170:173], v[70:73], v[154:157], v[162:165]
	v_mfma_f32_16x16x32_bf16 v[150:153], v[62:65], v[178:181], v[150:153]
	v_mfma_f32_16x16x32_bf16 v[146:149], v[70:73], v[178:181], v[146:149]
	v_mfma_f32_16x16x32_bf16 v[126:129], v[62:65], v[186:189], v[126:129]
	v_mfma_f32_16x16x32_bf16 v[122:125], v[70:73], v[186:189], v[122:125]
	v_mfma_f32_16x16x32_bf16 v[102:105], v[62:65], v[194:197], v[102:105]
	v_mfma_f32_16x16x32_bf16 v[98:101], v[70:73], v[194:197], v[98:101]
	v_mfma_f32_16x16x32_bf16 v[162:165], v[86:89], v[142:145], v[166:169]
	v_mfma_f32_16x16x32_bf16 v[130:133], v[106:109], v[142:145], v[130:133]
	v_mfma_f32_16x16x32_bf16 v[166:169], v[90:93], v[154:157], v[162:165]
	v_mfma_f32_16x16x32_bf16 v[162:165], v[110:113], v[154:157], v[130:133]
	v_mfma_f32_16x16x32_bf16 v[130:133], v[86:89], v[158:161], v[134:137]
	v_mfma_f32_16x16x32_bf16 v[142:145], v[90:93], v[178:181], v[130:133]
	v_mfma_f32_16x16x32_bf16 v[130:133], v[106:109], v[158:161], v[138:141]
	v_mfma_f32_16x16x32_bf16 v[118:121], v[86:89], v[182:185], v[118:121]
	v_mfma_f32_16x16x32_bf16 v[114:117], v[106:109], v[182:185], v[114:117]
	v_mfma_f32_16x16x32_bf16 v[94:97], v[86:89], v[190:193], v[94:97]
	v_mfma_f32_16x16x32_bf16 v[82:85], v[106:109], v[190:193], v[82:85]
	v_mfma_f32_16x16x32_bf16 v[138:141], v[110:113], v[178:181], v[130:133]
	v_mfma_f32_16x16x32_bf16 v[118:121], v[90:93], v[186:189], v[118:121]
	v_mfma_f32_16x16x32_bf16 v[114:117], v[110:113], v[186:189], v[114:117]
	v_mfma_f32_16x16x32_bf16 v[94:97], v[90:93], v[194:197], v[94:97]
	v_mfma_f32_16x16x32_bf16 v[82:85], v[110:113], v[194:197], v[82:85]
	s_barrier
	s_add_u32 s42, s40, 0x80
	s_addc_u32 s43, s41, 0
	ds_read_b128 v[130:133], v237 offset:49152
	ds_read_b128 v[134:137], v237 offset:50176
	ds_read_b128 v[154:157], v237 offset:51200
	ds_read_b128 v[158:161], v237 offset:52224
	ds_read_b128 v[178:181], v237 offset:53248
	ds_read_b128 v[182:185], v237 offset:54272
	ds_read_b128 v[186:189], v237 offset:55296
	ds_read_b128 v[190:193], v237 offset:56320
	s_add_i32 s58, s58, s45
	v_lshl_add_u64 v[194:195], s[42:43], 0, v[202:203]
	s_mov_b32 m0, s58
	s_add_u32 s42, s42, 0x40000
	global_load_lds_dwordx4 v[194:195], off
	s_addc_u32 s43, s43, 0
	s_add_i32 m0, s58, 0x2000
	s_add_u32 s40, s40, 0x80080
	s_addc_u32 s41, s41, 0
	v_lshl_add_u64 v[194:195], s[42:43], 0, v[202:203]
	global_load_lds_dwordx4 v[194:195], off
	s_add_i32 s42, s59, s45
	v_lshl_add_u64 v[194:195], s[40:41], 0, v[202:203]
	s_add_u32 s40, s40, 0x40000
	s_mov_b32 m0, s42
	s_addc_u32 s41, s41, 0
	global_load_lds_dwordx4 v[194:195], off
	s_add_i32 m0, s42, 0x2000
	v_lshl_add_u64 v[194:195], s[40:41], 0, v[202:203]
	global_load_lds_dwordx4 v[194:195], off
	s_mov_b32 m0, s50
	v_lshl_add_u64 v[194:195], s[38:39], 0, v[208:209]
	s_add_u32 s38, s38, 0x40000
	s_addc_u32 s39, s39, 0
	global_load_lds_dwordx4 v[194:195], off
	s_mov_b32 m0, s51
	v_lshl_add_u64 v[194:195], s[38:39], 0, v[208:209]
	global_load_lds_dwordx4 v[194:195], off
	s_waitcnt vmcnt(8)
	s_waitcnt lgkmcnt(0)
	s_barrier
	v_mfma_f32_16x16x32_bf16 v[78:81], v[58:61], v[130:133], v[78:81]
	v_mfma_f32_16x16x32_bf16 v[74:77], v[66:69], v[130:133], v[74:77]
	v_mfma_f32_16x16x32_bf16 v[54:57], v[58:61], v[154:157], v[54:57]
	v_mfma_f32_16x16x32_bf16 v[50:53], v[66:69], v[154:157], v[50:53]
	v_mfma_f32_16x16x32_bf16 v[30:33], v[58:61], v[178:181], v[30:33]
	v_mfma_f32_16x16x32_bf16 v[26:29], v[66:69], v[178:181], v[26:29]
	v_mfma_f32_16x16x32_bf16 v[14:17], v[58:61], v[186:189], v[14:17]
	v_mfma_f32_16x16x32_bf16 v[10:13], v[66:69], v[186:189], v[10:13]
	v_mfma_f32_16x16x32_bf16 v[78:81], v[62:65], v[134:137], v[78:81]
	v_mfma_f32_16x16x32_bf16 v[74:77], v[70:73], v[134:137], v[74:77]
	v_mfma_f32_16x16x32_bf16 v[54:57], v[62:65], v[158:161], v[54:57]
	v_mfma_f32_16x16x32_bf16 v[50:53], v[70:73], v[158:161], v[50:53]
	v_mfma_f32_16x16x32_bf16 v[30:33], v[62:65], v[182:185], v[30:33]
	v_mfma_f32_16x16x32_bf16 v[26:29], v[70:73], v[182:185], v[26:29]
	v_mfma_f32_16x16x32_bf16 v[14:17], v[62:65], v[190:193], v[14:17]
	v_mfma_f32_16x16x32_bf16 v[10:13], v[70:73], v[190:193], v[10:13]
	v_mfma_f32_16x16x32_bf16 v[42:45], v[86:89], v[130:133], v[42:45]
	v_mfma_f32_16x16x32_bf16 v[62:65], v[90:93], v[134:137], v[42:45]
	v_mfma_f32_16x16x32_bf16 v[42:45], v[106:109], v[130:133], v[46:49]
	v_mfma_f32_16x16x32_bf16 v[38:41], v[86:89], v[154:157], v[38:41]
	v_mfma_f32_16x16x32_bf16 v[34:37], v[106:109], v[154:157], v[34:37]
	v_mfma_f32_16x16x32_bf16 v[22:25], v[86:89], v[178:181], v[22:25]
	v_mfma_f32_16x16x32_bf16 v[18:21], v[106:109], v[178:181], v[18:21]
	v_mfma_f32_16x16x32_bf16 v[6:9], v[86:89], v[186:189], v[6:9]
	v_mfma_f32_16x16x32_bf16 v[2:5], v[106:109], v[186:189], v[2:5]
	v_mfma_f32_16x16x32_bf16 v[58:61], v[110:113], v[134:137], v[42:45]
	v_mfma_f32_16x16x32_bf16 v[38:41], v[90:93], v[158:161], v[38:41]
	v_mfma_f32_16x16x32_bf16 v[34:37], v[110:113], v[158:161], v[34:37]
	v_mfma_f32_16x16x32_bf16 v[22:25], v[90:93], v[182:185], v[22:25]
	v_mfma_f32_16x16x32_bf16 v[18:21], v[110:113], v[182:185], v[18:21]
	v_mfma_f32_16x16x32_bf16 v[6:9], v[90:93], v[190:193], v[6:9]
	v_mfma_f32_16x16x32_bf16 v[2:5], v[110:113], v[190:193], v[2:5]
	s_barrier
	s_add_i32 s57, s57, 2
	s_add_u32 s19, s19, 0x100
	s_addc_u32 s54, s54, 0
	s_add_u32 s55, s55, 0x100
	s_addc_u32 s56, s56, 0
	s_cmp_gt_u32 s57, 29
	s_cbranch_scc1 .Lpeel0_exit

.LBB0_1025:
	s_mov_b32 s10, 0
	v_mov_b32_e32 v2, 0
	v_mov_b32_e32 v3, 0
	v_mov_b32_e32 v4, 0
	v_mov_b32_e32 v5, 0
	v_mov_b32_e32 v6, 0
	v_mov_b32_e32 v7, 0
	v_mov_b32_e32 v8, 0
	v_mov_b32_e32 v9, 0
	s_waitcnt vmcnt(14)
	s_add_i32 s28, s10, 2
	s_cmp_eq_u32 s71, s10
	s_cselect_b32 s46, s4, s74
	s_cselect_b32 s47, s5, s75
	s_cselect_b32 s44, s42, s72
	s_cselect_b32 s45, s43, s73
	s_add_u32 s10, s46, 0x80
	s_addc_u32 s11, s47, 0
	s_add_i32 s29, 0, 0x10000
	s_add_i32 s78, 0, 0x14000
	v_add_u32_e32 v142, s29, v179
	v_add_u32_e32 v160, s78, v179
	ds_read_b128 v[130:133], v142
	ds_read_b128 v[134:137], v142 offset:1024
	ds_read_b128 v[138:141], v142 offset:2048
	ds_read_b128 v[142:145], v142 offset:3072
	ds_read_b128 v[146:149], v160
	ds_read_b128 v[150:153], v160 offset:1024
	ds_read_b128 v[154:157], v160 offset:2048
	ds_read_b128 v[160:163], v160 offset:3072
	s_add_u32 s76, s74, 0x7ff80
	v_add_u32_e32 v200, 0, v178
	s_addc_u32 s77, s75, 0
	ds_read_b128 v[164:167], v200
	ds_read_b128 v[168:171], v200 offset:1024
	ds_read_b128 v[172:175], v200 offset:2048
	ds_read_b128 v[180:183], v200 offset:3072
	ds_read_b128 v[184:187], v200 offset:4096
	ds_read_b128 v[188:191], v200 offset:5120
	ds_read_b128 v[192:195], v200 offset:6144
	ds_read_b128 v[196:199], v200 offset:7168
	s_add_i32 m0, s49, 0xc000
	v_lshl_add_u64 v[176:177], s[76:77], 0, v[158:159]
	s_add_u32 s76, s76, 0x40000
	s_addc_u32 s77, s77, 0
	global_load_lds_dwordx4 v[176:177], off
	s_add_i32 m0, s49, 0xe000
	v_lshl_add_u64 v[176:177], s[76:77], 0, v[158:159]
	global_load_lds_dwordx4 v[176:177], off
	s_waitcnt vmcnt(8)
	s_waitcnt lgkmcnt(0)
	s_barrier
	v_mfma_i32_16x16x64_i8 v[126:129], v[130:133], v[164:167], 0
	v_mfma_i32_16x16x64_i8 v[122:125], v[138:141], v[164:167], 0
	v_mfma_i32_16x16x64_i8 v[118:121], v[130:133], v[172:175], 0
	v_mfma_i32_16x16x64_i8 v[114:117], v[138:141], v[172:175], 0
	v_mfma_i32_16x16x64_i8 v[102:105], v[130:133], v[184:187], 0
	v_mfma_i32_16x16x64_i8 v[98:101], v[138:141], v[184:187], 0
	v_mfma_i32_16x16x64_i8 v[86:89], v[130:133], v[192:195], 0
	v_mfma_i32_16x16x64_i8 v[82:85], v[138:141], v[192:195], 0
	v_mfma_i32_16x16x64_i8 v[126:129], v[134:137], v[168:171], v[126:129]
	v_mfma_i32_16x16x64_i8 v[122:125], v[142:145], v[168:171], v[122:125]
	v_mfma_i32_16x16x64_i8 v[118:121], v[134:137], v[180:183], v[118:121]
	v_mfma_i32_16x16x64_i8 v[114:117], v[142:145], v[180:183], v[114:117]
	v_mfma_i32_16x16x64_i8 v[102:105], v[134:137], v[188:191], v[102:105]
	v_mfma_i32_16x16x64_i8 v[98:101], v[142:145], v[188:191], v[98:101]
	v_mfma_i32_16x16x64_i8 v[86:89], v[134:137], v[196:199], v[86:89]
	v_mfma_i32_16x16x64_i8 v[82:85], v[142:145], v[196:199], v[82:85]
	v_mfma_i32_16x16x64_i8 v[110:113], v[146:149], v[164:167], 0
	v_mfma_i32_16x16x64_i8 v[106:109], v[154:157], v[164:167], 0
	v_mfma_i32_16x16x64_i8 v[94:97], v[146:149], v[172:175], 0
	v_mfma_i32_16x16x64_i8 v[90:93], v[154:157], v[172:175], 0
	v_mfma_i32_16x16x64_i8 v[78:81], v[146:149], v[184:187], 0
	v_mfma_i32_16x16x64_i8 v[74:77], v[154:157], v[184:187], 0
	v_mfma_i32_16x16x64_i8 v[70:73], v[146:149], v[192:195], 0
	v_mfma_i32_16x16x64_i8 v[66:69], v[154:157], v[192:195], 0
	v_mfma_i32_16x16x64_i8 v[110:113], v[150:153], v[168:171], v[110:113]
	v_mfma_i32_16x16x64_i8 v[106:109], v[160:163], v[168:171], v[106:109]
	v_mfma_i32_16x16x64_i8 v[94:97], v[150:153], v[180:183], v[94:97]
	v_mfma_i32_16x16x64_i8 v[90:93], v[160:163], v[180:183], v[90:93]
	v_mfma_i32_16x16x64_i8 v[78:81], v[150:153], v[188:191], v[78:81]
	v_mfma_i32_16x16x64_i8 v[74:77], v[160:163], v[188:191], v[74:77]
	v_mfma_i32_16x16x64_i8 v[70:73], v[150:153], v[196:199], v[70:73]
	v_mfma_i32_16x16x64_i8 v[66:69], v[160:163], v[196:199], v[66:69]
	s_barrier
	s_mov_b64 s[76:77], s[44:45]
	ds_read_b128 v[164:167], v200 offset:16384
	ds_read_b128 v[168:171], v200 offset:17408
	ds_read_b128 v[172:175], v200 offset:18432
	ds_read_b128 v[180:183], v200 offset:19456
	ds_read_b128 v[184:187], v200 offset:20480
	ds_read_b128 v[188:191], v200 offset:21504
	ds_read_b128 v[192:195], v200 offset:22528
	ds_read_b128 v[196:199], v200 offset:23552
	s_add_i32 s29, s29, s48
	v_lshl_add_u64 v[176:177], s[76:77], 0, v[202:203]
	s_add_u32 s76, s76, 0x30000
	s_mov_b32 m0, s29
	s_addc_u32 s77, s77, 0
	global_load_lds_dwordx4 v[176:177], off
	s_add_i32 m0, s29, 0x2000
	v_lshl_add_u64 v[176:177], s[76:77], 0, v[202:203]
	s_add_u32 s76, s44, 0x60000
	s_addc_u32 s77, s45, 0
	global_load_lds_dwordx4 v[176:177], off
	s_add_i32 s29, s78, s48
	v_lshl_add_u64 v[176:177], s[76:77], 0, v[202:203]
	s_add_u32 s76, s76, 0x30000
	s_mov_b32 m0, s29
	s_addc_u32 s77, s77, 0
	global_load_lds_dwordx4 v[176:177], off
	s_add_i32 m0, s29, 0x2000
	v_lshl_add_u64 v[176:177], s[76:77], 0, v[202:203]
	s_mov_b64 s[76:77], s[46:47]
	global_load_lds_dwordx4 v[176:177], off
	s_mov_b32 m0, s49
	v_lshl_add_u64 v[176:177], s[76:77], 0, v[158:159]
	s_add_u32 s76, s76, 0x40000
	s_addc_u32 s77, s77, 0
	global_load_lds_dwordx4 v[176:177], off
	s_mov_b32 m0, s50
	v_lshl_add_u64 v[176:177], s[76:77], 0, v[158:159]
	global_load_lds_dwordx4 v[176:177], off
	s_waitcnt vmcnt(8)
	s_waitcnt lgkmcnt(0)
	s_barrier
	v_mfma_i32_16x16x64_i8 v[62:65], v[130:133], v[164:167], 0
	v_mfma_i32_16x16x64_i8 v[58:61], v[138:141], v[164:167], 0
	v_mfma_i32_16x16x64_i8 v[54:57], v[130:133], v[172:175], 0
	v_mfma_i32_16x16x64_i8 v[50:53], v[138:141], v[172:175], 0
	v_mfma_i32_16x16x64_i8 v[38:41], v[130:133], v[184:187], 0
	v_mfma_i32_16x16x64_i8 v[34:37], v[138:141], v[184:187], 0
	v_mfma_i32_16x16x64_i8 v[14:17], v[130:133], v[192:195], 0
	v_mfma_i32_16x16x64_i8 v[10:13], v[138:141], v[192:195], 0
	v_mfma_i32_16x16x64_i8 v[62:65], v[134:137], v[168:171], v[62:65]
	v_mfma_i32_16x16x64_i8 v[58:61], v[142:145], v[168:171], v[58:61]
	v_mfma_i32_16x16x64_i8 v[54:57], v[134:137], v[180:183], v[54:57]
	v_mfma_i32_16x16x64_i8 v[50:53], v[142:145], v[180:183], v[50:53]
	v_mfma_i32_16x16x64_i8 v[38:41], v[134:137], v[188:191], v[38:41]
	v_mfma_i32_16x16x64_i8 v[34:37], v[142:145], v[188:191], v[34:37]
	v_mfma_i32_16x16x64_i8 v[14:17], v[134:137], v[196:199], v[14:17]
	v_mfma_i32_16x16x64_i8 v[10:13], v[142:145], v[196:199], v[10:13]
	v_mfma_i32_16x16x64_i8 v[46:49], v[146:149], v[164:167], 0
	v_mfma_i32_16x16x64_i8 v[42:45], v[154:157], v[164:167], 0
	v_mfma_i32_16x16x64_i8 v[30:33], v[146:149], v[172:175], 0
	v_mfma_i32_16x16x64_i8 v[26:29], v[154:157], v[172:175], 0
	v_mfma_i32_16x16x64_i8 v[22:25], v[146:149], v[184:187], 0
	v_mfma_i32_16x16x64_i8 v[18:21], v[154:157], v[184:187], 0
	v_mfma_i32_16x16x64_i8 v[6:9], v[146:149], v[192:195], v[6:9]
	v_mfma_i32_16x16x64_i8 v[2:5], v[154:157], v[192:195], v[2:5]
	v_mfma_i32_16x16x64_i8 v[46:49], v[150:153], v[168:171], v[46:49]
	v_mfma_i32_16x16x64_i8 v[42:45], v[160:163], v[168:171], v[42:45]
	v_mfma_i32_16x16x64_i8 v[30:33], v[150:153], v[180:183], v[30:33]
	v_mfma_i32_16x16x64_i8 v[26:29], v[160:163], v[180:183], v[26:29]
	v_mfma_i32_16x16x64_i8 v[22:25], v[150:153], v[188:191], v[22:25]
	v_mfma_i32_16x16x64_i8 v[18:21], v[160:163], v[188:191], v[18:21]
	v_mfma_i32_16x16x64_i8 v[6:9], v[150:153], v[196:199], v[6:9]
	v_mfma_i32_16x16x64_i8 v[2:5], v[160:163], v[196:199], v[2:5]
	s_barrier
	s_add_i32 s29, 0, 0x18000
	s_add_i32 s76, 0, 0x1c000
	v_add_u32_e32 v142, s29, v179
	v_add_u32_e32 v160, s76, v179
	ds_read_b128 v[130:133], v142
	ds_read_b128 v[134:137], v142 offset:1024
	ds_read_b128 v[138:141], v142 offset:2048
	ds_read_b128 v[142:145], v142 offset:3072
	ds_read_b128 v[146:149], v160
	ds_read_b128 v[150:153], v160 offset:1024
	ds_read_b128 v[154:157], v160 offset:2048
	ds_read_b128 v[160:163], v160 offset:3072
	s_add_u32 s46, s46, 0x80000
	s_addc_u32 s47, s47, 0
	ds_read_b128 v[164:167], v200 offset:32768
	ds_read_b128 v[168:171], v200 offset:33792
	ds_read_b128 v[172:175], v200 offset:34816
	ds_read_b128 v[180:183], v200 offset:35840
	ds_read_b128 v[184:187], v200 offset:36864
	ds_read_b128 v[188:191], v200 offset:37888
	ds_read_b128 v[192:195], v200 offset:38912
	ds_read_b128 v[196:199], v200 offset:39936
	s_mov_b32 m0, s51
	v_lshl_add_u64 v[176:177], s[46:47], 0, v[158:159]
	s_add_u32 s46, s46, 0x40000
	s_addc_u32 s47, s47, 0
	global_load_lds_dwordx4 v[176:177], off
	s_mov_b32 m0, s52
	v_lshl_add_u64 v[176:177], s[46:47], 0, v[158:159]
	global_load_lds_dwordx4 v[176:177], off
	s_waitcnt vmcnt(8)
	s_waitcnt lgkmcnt(0)
	s_barrier
	v_mfma_i32_16x16x64_i8 v[126:129], v[130:133], v[164:167], v[126:129]
	v_mfma_i32_16x16x64_i8 v[122:125], v[138:141], v[164:167], v[122:125]
	v_mfma_i32_16x16x64_i8 v[118:121], v[130:133], v[172:175], v[118:121]
	v_mfma_i32_16x16x64_i8 v[114:117], v[138:141], v[172:175], v[114:117]
	v_mfma_i32_16x16x64_i8 v[102:105], v[130:133], v[184:187], v[102:105]
	v_mfma_i32_16x16x64_i8 v[98:101], v[138:141], v[184:187], v[98:101]
	v_mfma_i32_16x16x64_i8 v[86:89], v[130:133], v[192:195], v[86:89]
	v_mfma_i32_16x16x64_i8 v[82:85], v[138:141], v[192:195], v[82:85]
	v_mfma_i32_16x16x64_i8 v[126:129], v[134:137], v[168:171], v[126:129]
	v_mfma_i32_16x16x64_i8 v[122:125], v[142:145], v[168:171], v[122:125]
	v_mfma_i32_16x16x64_i8 v[118:121], v[134:137], v[180:183], v[118:121]
	v_mfma_i32_16x16x64_i8 v[114:117], v[142:145], v[180:183], v[114:117]
	v_mfma_i32_16x16x64_i8 v[102:105], v[134:137], v[188:191], v[102:105]
	v_mfma_i32_16x16x64_i8 v[98:101], v[142:145], v[188:191], v[98:101]
	v_mfma_i32_16x16x64_i8 v[86:89], v[134:137], v[196:199], v[86:89]
	v_mfma_i32_16x16x64_i8 v[82:85], v[142:145], v[196:199], v[82:85]
	v_mfma_i32_16x16x64_i8 v[110:113], v[146:149], v[164:167], v[110:113]
	v_mfma_i32_16x16x64_i8 v[106:109], v[154:157], v[164:167], v[106:109]
	v_mfma_i32_16x16x64_i8 v[94:97], v[146:149], v[172:175], v[94:97]
	v_mfma_i32_16x16x64_i8 v[90:93], v[154:157], v[172:175], v[90:93]
	v_mfma_i32_16x16x64_i8 v[78:81], v[146:149], v[184:187], v[78:81]
	v_mfma_i32_16x16x64_i8 v[74:77], v[154:157], v[184:187], v[74:77]
	v_mfma_i32_16x16x64_i8 v[70:73], v[146:149], v[192:195], v[70:73]
	v_mfma_i32_16x16x64_i8 v[66:69], v[154:157], v[192:195], v[66:69]
	v_mfma_i32_16x16x64_i8 v[110:113], v[150:153], v[168:171], v[110:113]
	v_mfma_i32_16x16x64_i8 v[106:109], v[160:163], v[168:171], v[106:109]
	v_mfma_i32_16x16x64_i8 v[94:97], v[150:153], v[180:183], v[94:97]
	v_mfma_i32_16x16x64_i8 v[90:93], v[160:163], v[180:183], v[90:93]
	v_mfma_i32_16x16x64_i8 v[78:81], v[150:153], v[188:191], v[78:81]
	v_mfma_i32_16x16x64_i8 v[74:77], v[160:163], v[188:191], v[74:77]
	v_mfma_i32_16x16x64_i8 v[70:73], v[150:153], v[196:199], v[70:73]
	v_mfma_i32_16x16x64_i8 v[66:69], v[160:163], v[196:199], v[66:69]
	s_barrier
	s_add_u32 s46, s44, 0x80
	s_addc_u32 s47, s45, 0
	ds_read_b128 v[164:167], v200 offset:49152
	ds_read_b128 v[168:171], v200 offset:50176
	ds_read_b128 v[172:175], v200 offset:51200
	ds_read_b128 v[180:183], v200 offset:52224
	ds_read_b128 v[184:187], v200 offset:53248
	ds_read_b128 v[188:191], v200 offset:54272
	ds_read_b128 v[192:195], v200 offset:55296
	ds_read_b128 v[196:199], v200 offset:56320
	s_add_i32 s29, s29, s48
	v_lshl_add_u64 v[176:177], s[46:47], 0, v[202:203]
	s_mov_b32 m0, s29
	s_add_u32 s46, s46, 0x30000
	global_load_lds_dwordx4 v[176:177], off
	s_addc_u32 s47, s47, 0
	s_add_i32 m0, s29, 0x2000
	s_add_u32 s44, s44, 0x60080
	s_addc_u32 s45, s45, 0
	v_lshl_add_u64 v[176:177], s[46:47], 0, v[202:203]
	global_load_lds_dwordx4 v[176:177], off
	s_add_i32 s29, s76, s48
	v_lshl_add_u64 v[176:177], s[44:45], 0, v[202:203]
	s_add_u32 s44, s44, 0x30000
	s_mov_b32 m0, s29
	s_addc_u32 s45, s45, 0
	global_load_lds_dwordx4 v[176:177], off
	s_add_i32 m0, s29, 0x2000
	v_lshl_add_u64 v[176:177], s[44:45], 0, v[202:203]
	global_load_lds_dwordx4 v[176:177], off
	s_mov_b32 m0, s53
	v_lshl_add_u64 v[176:177], s[10:11], 0, v[158:159]
	s_add_u32 s10, s10, 0x40000
	s_addc_u32 s11, s11, 0
	global_load_lds_dwordx4 v[176:177], off
	s_mov_b32 m0, s54
	v_lshl_add_u64 v[176:177], s[10:11], 0, v[158:159]
	global_load_lds_dwordx4 v[176:177], off
	s_waitcnt vmcnt(8)
	s_waitcnt lgkmcnt(0)
	s_barrier
	v_mfma_i32_16x16x64_i8 v[62:65], v[130:133], v[164:167], v[62:65]
	v_mfma_i32_16x16x64_i8 v[58:61], v[138:141], v[164:167], v[58:61]
	v_mfma_i32_16x16x64_i8 v[54:57], v[130:133], v[172:175], v[54:57]
	v_mfma_i32_16x16x64_i8 v[50:53], v[138:141], v[172:175], v[50:53]
	v_mfma_i32_16x16x64_i8 v[38:41], v[130:133], v[184:187], v[38:41]
	v_mfma_i32_16x16x64_i8 v[34:37], v[138:141], v[184:187], v[34:37]
	v_mfma_i32_16x16x64_i8 v[14:17], v[130:133], v[192:195], v[14:17]
	v_mfma_i32_16x16x64_i8 v[10:13], v[138:141], v[192:195], v[10:13]
	v_mfma_i32_16x16x64_i8 v[62:65], v[134:137], v[168:171], v[62:65]
	v_mfma_i32_16x16x64_i8 v[58:61], v[142:145], v[168:171], v[58:61]
	v_mfma_i32_16x16x64_i8 v[54:57], v[134:137], v[180:183], v[54:57]
	v_mfma_i32_16x16x64_i8 v[50:53], v[142:145], v[180:183], v[50:53]
	v_mfma_i32_16x16x64_i8 v[38:41], v[134:137], v[188:191], v[38:41]
	v_mfma_i32_16x16x64_i8 v[34:37], v[142:145], v[188:191], v[34:37]
	v_mfma_i32_16x16x64_i8 v[14:17], v[134:137], v[196:199], v[14:17]
	v_mfma_i32_16x16x64_i8 v[10:13], v[142:145], v[196:199], v[10:13]
	v_mfma_i32_16x16x64_i8 v[46:49], v[146:149], v[164:167], v[46:49]
	v_mfma_i32_16x16x64_i8 v[42:45], v[154:157], v[164:167], v[42:45]
	v_mfma_i32_16x16x64_i8 v[30:33], v[146:149], v[172:175], v[30:33]
	v_mfma_i32_16x16x64_i8 v[26:29], v[154:157], v[172:175], v[26:29]
	v_mfma_i32_16x16x64_i8 v[22:25], v[146:149], v[184:187], v[22:25]
	v_mfma_i32_16x16x64_i8 v[18:21], v[154:157], v[184:187], v[18:21]
	v_mfma_i32_16x16x64_i8 v[6:9], v[146:149], v[192:195], v[6:9]
	v_mfma_i32_16x16x64_i8 v[2:5], v[154:157], v[192:195], v[2:5]
	v_mfma_i32_16x16x64_i8 v[46:49], v[150:153], v[168:171], v[46:49]
	v_mfma_i32_16x16x64_i8 v[42:45], v[160:163], v[168:171], v[42:45]
	v_mfma_i32_16x16x64_i8 v[30:33], v[150:153], v[180:183], v[30:33]
	v_mfma_i32_16x16x64_i8 v[26:29], v[160:163], v[180:183], v[26:29]
	v_mfma_i32_16x16x64_i8 v[22:25], v[150:153], v[188:191], v[22:25]
	v_mfma_i32_16x16x64_i8 v[18:21], v[160:163], v[188:191], v[18:21]
	v_mfma_i32_16x16x64_i8 v[6:9], v[150:153], v[196:199], v[6:9]
	v_mfma_i32_16x16x64_i8 v[2:5], v[160:163], v[196:199], v[2:5]
	s_barrier
	s_add_u32 s74, s74, 0x100
	s_addc_u32 s75, s75, 0
	s_add_u32 s72, s72, 0x100
	s_addc_u32 s73, s73, 0
	s_cmp_ge_i32 s28, s69
	s_mov_b32 s10, s28
	s_cbranch_scc1 .Lpeel2_exit
